# ctx rows of the gated merge GEMM also moved to a sliver GEMM with 4 per-branch accumulators and one pass over the gates
# speedup vs baseline: 1.0183x; 1.0183x over previous
.LBB0_1165:
	v_mov_b32_e32 v0, s15
	v_mov_b32_e32 v2, s14
	s_cmp_gt_i32 s87, 3
	v_readfirstlane_b32 s14, v2
	v_readlane_b32 s22, v254, 56
	v_mov_b32_e32 v2, s12
	v_writelane_b32 v255, s14, 10
	v_readfirstlane_b32 s14, v0
	v_mov_b32_e32 v0, s13
	s_cselect_b64 s[20:21], -1, 0
	v_readlane_b32 s23, v254, 57
	v_writelane_b32 v255, s14, 11
	s_and_b64 s[20:21], s[22:23], s[20:21]
	v_readfirstlane_b32 s12, v2
	v_mov_b32_e32 v2, s8
	s_and_b64 s[20:21], s[20:21], exec
	v_writelane_b32 v255, s12, 12
	v_readfirstlane_b32 s12, v0
	v_mov_b32_e32 v0, s9
	s_cselect_b32 s81, 64, 0x48
	s_bitcmp1_b32 s87, 0
	s_cselect_b32 s81, 64, s81
	s_cmp_eq_u32 s87, 4
	s_cselect_b32 s81, 64, s81
	v_writelane_b32 v255, s12, 13
	v_readfirstlane_b32 s8, v2
	v_mov_b32_e32 v2, s40
	s_lshr_b32 s91, s1, 8
	v_writelane_b32 v255, s8, 14
	v_readfirstlane_b32 s8, v0
	v_mov_b32_e32 v0, s41
	s_cmpk_eq_i32 s1, 0x1800
	v_writelane_b32 v255, s8, 15
	v_readfirstlane_b32 s8, v2
	s_cselect_b64 s[14:15], -1, 0
	s_mul_i32 s46, s91, s81
	v_writelane_b32 v255, s8, 16
	v_readfirstlane_b32 s8, v0
	v_mov_b32_e32 v0, s88
	v_mov_b32_e32 v14, v247
	v_writelane_b32 v255, s8, 17
	s_and_b64 s[8:9], s[14:15], exec
	s_cselect_b32 s12, 8, 4
	s_cmpk_eq_i32 s4, 0xb00
	s_cselect_b64 s[22:23], -1, 0
	s_and_b64 s[8:9], s[22:23], exec
	s_cselect_b32 s12, 2, s12
	s_cmpk_eq_i32 s1, 0x1600
	s_cselect_b64 s[24:25], -1, 0
	v_readfirstlane_b32 s90, v0
	s_and_b64 s[8:9], s[24:25], exec
	s_cselect_b32 s92, 4, s12
	s_cmp_lt_i32 s90, s46
	s_mul_i32 s38, s78, s79
	s_cselect_b64 s[12:13], -1, 0
	s_cmp_ge_i32 s90, s46
	v_readfirstlane_b32 s20, v14
	s_cbranch_scc0 .LBB0_1223
	s_sub_u32 s28, s90, s46
	s_subb_u32 s29, 0, 0
	v_mov_b32_e32 v0, s38
	v_cmp_lt_i64_e32 vcc, s[28:29], v[0:1]
	s_mov_b64 s[8:9], 0
	s_and_b64 vcc, exec, vcc
	s_mov_b64 s[26:27], 0
	s_cbranch_vccz .LBB0_1168
	s_sext_i32_i16 s18, s28
	s_bfe_u32 s18, s18, 0x3001c
	s_add_i32 s18, s28, s18
	s_sext_i32_i16 s21, s18
	s_and_b32 s18, s18, 0xfff8
	s_sub_i32 s18, s28, s18
	s_lshr_b32 s1, s38, 3
	s_ashr_i32 s21, s21, 3
	s_bfe_u32 s28, s18, 0x1000f
	s_and_b64 s[26:27], s[14:15], exec
	s_cselect_b32 s29, 3, 2
	s_and_b64 s[26:27], s[22:23], exec
	s_cselect_b32 s29, 1, s29
	s_and_b64 s[26:27], s[24:25], exec
	s_cselect_b32 s29, 2, s29
	s_lshl_b32 s30, s78, s29
	s_or_b32 s1, s28, s1
	s_mul_i32 s1, s1, s18
	s_sext_i32_i16 s18, s30
	v_cvt_f32_i32_e32 v0, s18
	s_add_i32 s1, s1, s21
	s_sext_i32_i16 s21, s1
	v_cvt_f32_i32_e32 v2, s21
	v_rcp_iflag_f32_e32 v3, v0
	s_xor_b32 s18, s21, s18
	s_ashr_i32 s18, s18, 30
	s_or_b32 s18, s18, 1
	v_mul_f32_e32 v3, v2, v3
	v_trunc_f32_e32 v3, v3
	v_fma_f32 v2, -v3, v0, v2
	v_cvt_i32_f32_e32 v3, v3
	v_cmp_ge_f32_e64 s[26:27], |v2|, |v0|
	s_and_b64 s[26:27], s[26:27], exec
	s_cselect_b32 s18, s18, 0
	v_readfirstlane_b32 s21, v3
	s_add_i32 s26, s21, s18
	s_sext_i32_i16 s18, s26
	s_lshl_b32 s18, s18, s29
	s_sub_i32 s21, s79, s18
	s_mul_i32 s26, s26, s30
	s_mov_b32 s94, 1
	s_min_i32 s21, s21, s92
	s_sub_i32 s29, s1, s26
	s_mov_b64 s[26:27], -1
	s_and_b64 vcc, exec, s[8:9]
	s_cbranch_vccz .LBB0_1170
	s_branch .LBB0_1169

.Lsl_entry:
	s_cmp_eq_u32 s87, 1
	s_cbranch_scc1 .Lsl_run
	s_cmp_eq_u32 s87, 4
	s_cbranch_scc1 .Lsl_chk
	s_cmp_eq_u32 s87, 5
	s_cbranch_scc1 .Lsl_chk
	s_cmp_eq_u32 s87, 7
	s_cbranch_scc0 .Lsl_skip

.Lsl_par5:
	s_mov_b32 s45, 16
	s_movk_i32 s43, 0x800
	s_add_u32 s4, s10, 0x9b00000
	s_addc_u32 s5, s11, 0
	s_add_u32 s6, s10, 0x2080000
	s_addc_u32 s7, s11, 0
	s_mov_b32 s42, 1.0
	s_mov_b32 s46, 0x5000
	s_cmp_eq_u32 s87, 5
	s_cbranch_scc1 .Lsl_par_done
	s_add_u32 s4, s10, 0x20300000
	s_addc_u32 s5, s11, 0
	s_add_u32 s6, s10, 0x1e80000
	s_addc_u32 s7, s11, 0
.Lsl_par_done:
	s_add_u32 s34, s10, 0x7300000
	s_addc_u32 s35, s11, 0
	v_readlane_b32 s47, v254, 38
	s_mul_i32 s47, s47, 0x51000
	s_add_u32 s47, s47, 0x48000
	s_add_u32 s47, s47, s46
	s_add_u32 s40, s10, 0x20700000
	s_addc_u32 s41, s11, 0
	s_add_u32 s40, s40, s47
	s_addc_u32 s41, s41, 0
	s_and_b32 s46, s88, 7
	s_lshr_b32 s47, s88, 3
	s_and_b32 s48, s46, 1
	s_lshl_b32 s48, s48, 2
	s_and_b32 s49, s47, 3
	s_add_u32 s48, s48, s49
	s_lshr_b32 s49, s46, 1
	s_lshl_b32 s49, s49, 3
	s_lshr_b32 s50, s47, 2
	s_add_u32 s49, s49, s50
	v_and_b32_e32 v71, 63, v247
	v_lshrrev_b32_e32 v72, 6, v247
	v_lshrrev_b32_e32 v73, 4, v71
	v_and_b32_e32 v73, 2, v73
	v_xor_b32_e32 v73, v73, v71
	v_readfirstlane_b32 s21, v72
	v_lshrrev_b32_e32 v74, 2, v73
	v_and_b32_e32 v75, 3, v73
	v_lshlrev_b32_e32 v75, 4, v75
	s_lshr_b32 s50, s21, 1
	s_lshl_b32 s50, s50, 4
	s_lshl_b32 s51, s49, 6
	s_add_u32 s50, s50, s51
	s_and_b32 s51, s21, 1
	s_lshl_b32 s51, s51, 6
	v_add_u32_e32 v64, s50, v74
	v_mul_lo_u32 v64, v64, s43
	v_add3_u32 v64, v64, v75, s51
	s_lshl_b32 s50, s48, 7
	s_lshl_b32 s51, s21, 4
	s_add_u32 s50, s50, s51
	v_add_u32_e32 v65, s50, v74
	v_mul_lo_u32 v65, v65, s43
	v_add_u32_e32 v65, v65, v75
	v_add_u32_e32 v66, 64, v65
	v_and_b32_e32 v73, 15, v71
	v_lshrrev_b32_e32 v74, 4, v71
	v_lshlrev_b32_e32 v75, 6, v73
	v_lshl_add_u32 v75, v74, 4, v75
	v_lshrrev_b32_e32 v72, 3, v73
	v_lshlrev_b32_e32 v72, 5, v72
	v_xor_b32_e32 v75, v75, v72
	s_lshr_b32 s50, s21, 2
	s_and_b32 s51, s21, 3
	s_lshl_b32 s52, s50, 12
	s_add_u32 s52, s52, 16
	v_add_u32_e32 v67, s52, v75
	s_lshl_b32 s52, s51, 12
	s_add_u32 s52, s52, 0x2010
	v_add_u32_e32 v68, s52, v75
	v_add_u32_e32 v69, 0xc000, v67
	v_add_u32_e32 v70, 0xc000, v68
	s_lshl_b32 s32, s21, 10
	s_add_u32 s32, s32, 16
	s_lshl_b32 s33, s21, 11
	s_add_u32 s33, s33, 0x2010
	s_lshl_b32 s52, s49, 6
	s_lshl_b32 s56, s50, 5
	s_add_u32 s52, s52, s56
	v_add_u32_e32 v71, s52, v73
	s_lshl_b32 s52, s48, 7
	s_lshl_b32 s56, s51, 5
	s_add_u32 s52, s52, s56
	v_lshl_add_u32 v72, v74, 2, s52
	v_lshl_add_u32 v100, v71, 10, v72
	v_lshlrev_b32_e32 v100, 2, v100
	v_lshlrev_b32_e32 v102, 2, v72
	v_add_u32_e32 v101, 0x10000, v100
	v_mov_b32_e32 v202, v102
	v_lshl_add_u32 v203, v71, 10, v72
	v_lshlrev_b32_e32 v203, 1, v203
	v_add_u32_e32 v204, 0x8000, v203
	v_mul_u32_u24_e32 v200, 0x3000, v71
	v_lshl_add_u32 v200, v72, 1, v200
	v_add_u32_e32 v201, 0x30000, v200
	s_cmp_eq_u32 s87, 4
	s_cbranch_scc1 .Lsb_start
	v_mov_b32_e32 v16, 0
	v_mov_b32_e32 v17, 0
	v_mov_b32_e32 v18, 0
	v_mov_b32_e32 v19, 0
	v_mov_b32_e32 v20, 0
	v_mov_b32_e32 v21, 0
	v_mov_b32_e32 v22, 0
	v_mov_b32_e32 v23, 0
	v_mov_b32_e32 v24, 0
	v_mov_b32_e32 v25, 0
	v_mov_b32_e32 v26, 0
	v_mov_b32_e32 v27, 0
	v_mov_b32_e32 v28, 0
	v_mov_b32_e32 v29, 0
	v_mov_b32_e32 v30, 0
	v_mov_b32_e32 v31, 0
	s_mov_b32 s14, s45
	s_add_i32 m0, s32, 0
	s_nop 0
	global_load_lds_dwordx4 v64, s[4:5]
	s_add_i32 m0, s33, 0
	s_nop 0
	global_load_lds_dwordx4 v65, s[6:7]
	s_add_i32 m0, s33, 1024
	s_nop 0
	global_load_lds_dwordx4 v66, s[6:7]
	s_add_u32 s4, s4, 0x80
	s_addc_u32 s5, s5, 0
	s_add_u32 s6, s6, 0x80
	s_addc_u32 s7, s7, 0
	s_add_i32 m0, s32, 24576
	s_nop 0
	global_load_lds_dwordx4 v64, s[4:5]
	s_add_i32 m0, s33, 24576
	s_nop 0
	global_load_lds_dwordx4 v65, s[6:7]
	s_add_i32 m0, s33, 25600
	s_nop 0
	global_load_lds_dwordx4 v66, s[6:7]
	s_add_u32 s4, s4, 0x80
	s_addc_u32 s5, s5, 0
	s_add_u32 s6, s6, 0x80
	s_addc_u32 s7, s7, 0
	s_add_i32 m0, s32, 49152
	s_nop 0
	global_load_lds_dwordx4 v64, s[4:5]
	s_add_i32 m0, s33, 49152
	s_nop 0
	global_load_lds_dwordx4 v65, s[6:7]
	s_add_i32 m0, s33, 50176
	s_nop 0
	global_load_lds_dwordx4 v66, s[6:7]
	s_add_u32 s4, s4, 0x80
	s_addc_u32 s5, s5, 0
	s_add_u32 s6, s6, 0x80
	s_addc_u32 s7, s7, 0

.Lsb_start:
	s_load_dwordx2 s[56:57], s[64:65], 0x60
	v_mov_b32_e32 v16, 0
	v_mov_b32_e32 v17, 0
	v_mov_b32_e32 v18, 0
	v_mov_b32_e32 v19, 0
	v_mov_b32_e32 v20, 0
	v_mov_b32_e32 v21, 0
	v_mov_b32_e32 v22, 0
	v_mov_b32_e32 v23, 0
	v_mov_b32_e32 v24, 0
	v_mov_b32_e32 v25, 0
	v_mov_b32_e32 v26, 0
	v_mov_b32_e32 v27, 0
	v_mov_b32_e32 v28, 0
	v_mov_b32_e32 v29, 0
	v_mov_b32_e32 v30, 0
	v_mov_b32_e32 v31, 0
	v_mov_b32_e32 v104, 0
	v_mov_b32_e32 v105, 0
	v_mov_b32_e32 v106, 0
	v_mov_b32_e32 v107, 0
	v_mov_b32_e32 v108, 0
	v_mov_b32_e32 v109, 0
	v_mov_b32_e32 v110, 0
	v_mov_b32_e32 v111, 0
	v_mov_b32_e32 v112, 0
	v_mov_b32_e32 v113, 0
	v_mov_b32_e32 v114, 0
	v_mov_b32_e32 v115, 0
	v_mov_b32_e32 v116, 0
	v_mov_b32_e32 v117, 0
	v_mov_b32_e32 v118, 0
	v_mov_b32_e32 v119, 0
	v_mov_b32_e32 v120, 0
	v_mov_b32_e32 v121, 0
	v_mov_b32_e32 v122, 0
	v_mov_b32_e32 v123, 0
	v_mov_b32_e32 v124, 0
	v_mov_b32_e32 v125, 0
	v_mov_b32_e32 v126, 0
	v_mov_b32_e32 v127, 0
	v_mov_b32_e32 v128, 0
	v_mov_b32_e32 v129, 0
	v_mov_b32_e32 v130, 0
	v_mov_b32_e32 v131, 0
	v_mov_b32_e32 v132, 0
	v_mov_b32_e32 v133, 0
	v_mov_b32_e32 v134, 0
	v_mov_b32_e32 v135, 0
	v_mov_b32_e32 v136, 0
	v_mov_b32_e32 v137, 0
	v_mov_b32_e32 v138, 0
	v_mov_b32_e32 v139, 0
	v_mov_b32_e32 v140, 0
	v_mov_b32_e32 v141, 0
	v_mov_b32_e32 v142, 0
	v_mov_b32_e32 v143, 0
	v_mov_b32_e32 v144, 0
	v_mov_b32_e32 v145, 0
	v_mov_b32_e32 v146, 0
	v_mov_b32_e32 v147, 0
	v_mov_b32_e32 v148, 0
	v_mov_b32_e32 v149, 0
	v_mov_b32_e32 v150, 0
	v_mov_b32_e32 v151, 0
	s_add_u32 s34, s10, 0x15f01000
	s_addc_u32 s35, s11, 0
	s_add_u32 s40, s34, 0x1000
	s_addc_u32 s41, s35, 0
	s_add_u32 s58, s10, 0x9b00000
	s_addc_u32 s59, s11, 0
	v_readlane_b32 s47, v254, 38
	s_lshl_b32 s47, s47, 14
	s_waitcnt lgkmcnt(0)
	s_add_u32 s56, s56, s47
	s_addc_u32 s57, s57, 0
	s_add_i32 m0, s32, 0
	s_nop 0
	global_load_lds_dwordx4 v64, s[4:5]
	s_add_i32 m0, s33, 0
	s_nop 0
	global_load_lds_dwordx4 v65, s[6:7]
	s_add_i32 m0, s33, 1024
	s_nop 0
	global_load_lds_dwordx4 v66, s[6:7]
	s_add_u32 s4, s4, 0x80
	s_addc_u32 s5, s5, 0
	s_add_u32 s6, s6, 0x80
	s_addc_u32 s7, s7, 0
	s_add_i32 m0, s32, 24576
	s_nop 0
	global_load_lds_dwordx4 v64, s[4:5]
	s_add_i32 m0, s33, 24576
	s_nop 0
	global_load_lds_dwordx4 v65, s[6:7]
	s_add_i32 m0, s33, 25600
	s_nop 0
	global_load_lds_dwordx4 v66, s[6:7]
	s_add_u32 s4, s4, 0x80
	s_addc_u32 s5, s5, 0
	s_add_u32 s6, s6, 0x80
	s_addc_u32 s7, s7, 0
	s_add_i32 m0, s32, 49152
	s_nop 0
	global_load_lds_dwordx4 v64, s[4:5]
	s_add_i32 m0, s33, 49152
	s_nop 0
	global_load_lds_dwordx4 v65, s[6:7]
	s_add_i32 m0, s33, 50176
	s_nop 0
	global_load_lds_dwordx4 v66, s[6:7]
	s_add_u32 s4, s4, 0x80
	s_addc_u32 s5, s5, 0
	s_add_u32 s6, s6, 0x80
	s_addc_u32 s7, s7, 0
	global_load_dwordx2 v[168:169], v200, s[34:35] offset:0
	global_load_dwordx2 v[170:171], v200, s[34:35] offset:32
	global_load_dwordx2 v[172:173], v201, s[34:35] offset:0
	global_load_dwordx2 v[174:175], v201, s[34:35] offset:32
	global_load_dwordx4 v[72:75], v202, s[56:57]
	global_load_dwordx4 v[76:79], v202, s[56:57] offset:64
	s_add_u32 s56, s56, 0x1000
	s_addc_u32 s57, s57, 0
	global_load_dwordx2 v[176:177], v200, s[34:35] offset:2048
	global_load_dwordx2 v[178:179], v200, s[34:35] offset:2080
	global_load_dwordx2 v[180:181], v201, s[34:35] offset:2048
	global_load_dwordx2 v[182:183], v201, s[34:35] offset:2080
	global_load_dwordx4 v[80:83], v202, s[56:57]
	global_load_dwordx4 v[84:87], v202, s[56:57] offset:64
	s_add_u32 s56, s56, 0x1000
	s_addc_u32 s57, s57, 0
	global_load_dwordx2 v[184:185], v200, s[40:41] offset:0
	global_load_dwordx2 v[186:187], v200, s[40:41] offset:32
	global_load_dwordx2 v[188:189], v201, s[40:41] offset:0
	global_load_dwordx2 v[190:191], v201, s[40:41] offset:32
	global_load_dwordx4 v[88:91], v202, s[56:57]
	global_load_dwordx4 v[92:95], v202, s[56:57] offset:64
	s_add_u32 s56, s56, 0x1000
	s_addc_u32 s57, s57, 0
	global_load_dwordx2 v[192:193], v200, s[40:41] offset:2048
	global_load_dwordx2 v[194:195], v200, s[40:41] offset:2080
	global_load_dwordx2 v[196:197], v201, s[40:41] offset:2048
	global_load_dwordx2 v[198:199], v201, s[40:41] offset:2080
	global_load_dwordx4 v[96:99], v202, s[56:57]
	global_load_dwordx4 v[100:103], v202, s[56:57] offset:64
	s_waitcnt vmcnt(30)
	s_barrier
	s_add_i32 m0, s32, 73728
	s_nop 0
	global_load_lds_dwordx4 v64, s[4:5]
	s_add_i32 m0, s33, 73728
	s_nop 0
	global_load_lds_dwordx4 v65, s[6:7]
	s_add_i32 m0, s33, 74752
	s_nop 0
	global_load_lds_dwordx4 v66, s[6:7]
	s_add_u32 s4, s4, 0x80
	s_addc_u32 s5, s5, 0
	s_add_u32 s6, s6, 0x80
	s_addc_u32 s7, s7, 0
	ds_read_b128 v[48:51], v68 offset:0
	ds_read_b128 v[56:59], v68 offset:2048
	ds_read_b128 v[32:35], v67 offset:0
	ds_read_b128 v[40:43], v67 offset:2048
	ds_read_b128 v[52:55], v68 offset:1024
	ds_read_b128 v[60:63], v68 offset:3072
	ds_read_b128 v[36:39], v67 offset:1024
	ds_read_b128 v[44:47], v67 offset:3072
	s_waitcnt lgkmcnt(4)
	v_mfma_f32_16x16x32_bf16 v[16:19], v[48:51], v[32:35], v[16:19]
	v_mfma_f32_16x16x32_bf16 v[20:23], v[56:59], v[32:35], v[20:23]
	v_mfma_f32_16x16x32_bf16 v[24:27], v[48:51], v[40:43], v[24:27]
	v_mfma_f32_16x16x32_bf16 v[28:31], v[56:59], v[40:43], v[28:31]
	s_waitcnt lgkmcnt(0)
	v_mfma_f32_16x16x32_bf16 v[16:19], v[52:55], v[36:39], v[16:19]
	v_mfma_f32_16x16x32_bf16 v[20:23], v[60:63], v[36:39], v[20:23]
	v_mfma_f32_16x16x32_bf16 v[24:27], v[52:55], v[44:47], v[24:27]
	v_mfma_f32_16x16x32_bf16 v[28:31], v[60:63], v[44:47], v[28:31]
	s_waitcnt vmcnt(30)
	s_barrier
	s_add_i32 m0, s32, 0
	s_nop 0
	global_load_lds_dwordx4 v64, s[4:5]
	s_add_i32 m0, s33, 0
	s_nop 0
	global_load_lds_dwordx4 v65, s[6:7]
	s_add_i32 m0, s33, 1024
	s_nop 0
	global_load_lds_dwordx4 v66, s[6:7]
	s_add_u32 s4, s4, 0x80
	s_addc_u32 s5, s5, 0
	s_add_u32 s6, s6, 0x80
	s_addc_u32 s7, s7, 0
	ds_read_b128 v[48:51], v68 offset:24576
	ds_read_b128 v[56:59], v68 offset:26624
	ds_read_b128 v[32:35], v67 offset:24576
	ds_read_b128 v[40:43], v67 offset:26624
	ds_read_b128 v[52:55], v68 offset:25600
	ds_read_b128 v[60:63], v68 offset:27648
	ds_read_b128 v[36:39], v67 offset:25600
	ds_read_b128 v[44:47], v67 offset:27648
	s_waitcnt lgkmcnt(4)
	v_mfma_f32_16x16x32_bf16 v[16:19], v[48:51], v[32:35], v[16:19]
	v_mfma_f32_16x16x32_bf16 v[20:23], v[56:59], v[32:35], v[20:23]
	v_mfma_f32_16x16x32_bf16 v[24:27], v[48:51], v[40:43], v[24:27]
	v_mfma_f32_16x16x32_bf16 v[28:31], v[56:59], v[40:43], v[28:31]
	s_waitcnt lgkmcnt(0)
	v_mfma_f32_16x16x32_bf16 v[16:19], v[52:55], v[36:39], v[16:19]
	v_mfma_f32_16x16x32_bf16 v[20:23], v[60:63], v[36:39], v[20:23]
	v_mfma_f32_16x16x32_bf16 v[24:27], v[52:55], v[44:47], v[24:27]
	v_mfma_f32_16x16x32_bf16 v[28:31], v[60:63], v[44:47], v[28:31]
	s_waitcnt vmcnt(30)
	s_barrier
	s_add_i32 m0, s32, 24576
	s_nop 0
	global_load_lds_dwordx4 v64, s[4:5]
	s_add_i32 m0, s33, 24576
	s_nop 0
	global_load_lds_dwordx4 v65, s[6:7]
	s_add_i32 m0, s33, 25600
	s_nop 0
	global_load_lds_dwordx4 v66, s[6:7]
	s_add_u32 s4, s4, 0x80
	s_addc_u32 s5, s5, 0
	s_add_u32 s6, s6, 0x80
	s_addc_u32 s7, s7, 0
	ds_read_b128 v[48:51], v70 offset:0
	ds_read_b128 v[56:59], v70 offset:2048
	ds_read_b128 v[32:35], v69 offset:0
	ds_read_b128 v[40:43], v69 offset:2048
	ds_read_b128 v[52:55], v70 offset:1024
	ds_read_b128 v[60:63], v70 offset:3072
	ds_read_b128 v[36:39], v69 offset:1024
	ds_read_b128 v[44:47], v69 offset:3072
	s_waitcnt lgkmcnt(4)
	v_mfma_f32_16x16x32_bf16 v[16:19], v[48:51], v[32:35], v[16:19]
	v_mfma_f32_16x16x32_bf16 v[20:23], v[56:59], v[32:35], v[20:23]
	v_mfma_f32_16x16x32_bf16 v[24:27], v[48:51], v[40:43], v[24:27]
	v_mfma_f32_16x16x32_bf16 v[28:31], v[56:59], v[40:43], v[28:31]
	s_waitcnt lgkmcnt(0)
	v_mfma_f32_16x16x32_bf16 v[16:19], v[52:55], v[36:39], v[16:19]
	v_mfma_f32_16x16x32_bf16 v[20:23], v[60:63], v[36:39], v[20:23]
	v_mfma_f32_16x16x32_bf16 v[24:27], v[52:55], v[44:47], v[24:27]
	v_mfma_f32_16x16x32_bf16 v[28:31], v[60:63], v[44:47], v[28:31]
	s_waitcnt vmcnt(6)
	s_barrier
	s_add_i32 m0, s32, 49152
	s_nop 0
	global_load_lds_dwordx4 v64, s[4:5]
	s_add_i32 m0, s33, 49152
	s_nop 0
	global_load_lds_dwordx4 v65, s[6:7]
	s_add_i32 m0, s33, 50176
	s_nop 0
	global_load_lds_dwordx4 v66, s[6:7]
	s_add_u32 s4, s4, 0x80
	s_addc_u32 s5, s5, 0
	s_add_u32 s6, s6, 0x80
	s_addc_u32 s7, s7, 0
	ds_read_b128 v[48:51], v70 offset:24576
	ds_read_b128 v[56:59], v70 offset:26624
	ds_read_b128 v[32:35], v69 offset:24576
	ds_read_b128 v[40:43], v69 offset:26624
	ds_read_b128 v[52:55], v70 offset:25600
	ds_read_b128 v[60:63], v70 offset:27648
	ds_read_b128 v[36:39], v69 offset:25600
	ds_read_b128 v[44:47], v69 offset:27648
	s_waitcnt lgkmcnt(4)
	v_mfma_f32_16x16x32_bf16 v[16:19], v[48:51], v[32:35], v[16:19]
	v_mfma_f32_16x16x32_bf16 v[20:23], v[56:59], v[32:35], v[20:23]
	v_mfma_f32_16x16x32_bf16 v[24:27], v[48:51], v[40:43], v[24:27]
	v_mfma_f32_16x16x32_bf16 v[28:31], v[56:59], v[40:43], v[28:31]
	s_waitcnt lgkmcnt(0)
	v_mfma_f32_16x16x32_bf16 v[16:19], v[52:55], v[36:39], v[16:19]
	v_mfma_f32_16x16x32_bf16 v[20:23], v[60:63], v[36:39], v[20:23]
	v_mfma_f32_16x16x32_bf16 v[24:27], v[52:55], v[44:47], v[24:27]
	v_mfma_f32_16x16x32_bf16 v[28:31], v[60:63], v[44:47], v[28:31]
	s_waitcnt vmcnt(6)
	s_barrier
	s_add_i32 m0, s32, 73728
	s_nop 0
	global_load_lds_dwordx4 v64, s[4:5]
	s_add_i32 m0, s33, 73728
	s_nop 0
	global_load_lds_dwordx4 v65, s[6:7]
	s_add_i32 m0, s33, 74752
	s_nop 0
	global_load_lds_dwordx4 v66, s[6:7]
	s_add_u32 s4, s4, 0x80
	s_addc_u32 s5, s5, 0
	s_add_u32 s6, s6, 0x80
	s_addc_u32 s7, s7, 0
	ds_read_b128 v[48:51], v68 offset:0
	ds_read_b128 v[56:59], v68 offset:2048
	ds_read_b128 v[32:35], v67 offset:0
	ds_read_b128 v[40:43], v67 offset:2048
	ds_read_b128 v[52:55], v68 offset:1024
	ds_read_b128 v[60:63], v68 offset:3072
	ds_read_b128 v[36:39], v67 offset:1024
	ds_read_b128 v[44:47], v67 offset:3072
	s_waitcnt lgkmcnt(4)
	v_mfma_f32_16x16x32_bf16 v[104:107], v[48:51], v[32:35], v[104:107]
	v_mfma_f32_16x16x32_bf16 v[108:111], v[56:59], v[32:35], v[108:111]
	v_mfma_f32_16x16x32_bf16 v[112:115], v[48:51], v[40:43], v[112:115]
	v_mfma_f32_16x16x32_bf16 v[116:119], v[56:59], v[40:43], v[116:119]
	s_waitcnt lgkmcnt(0)
	v_mfma_f32_16x16x32_bf16 v[104:107], v[52:55], v[36:39], v[104:107]
	v_mfma_f32_16x16x32_bf16 v[108:111], v[60:63], v[36:39], v[108:111]
	v_mfma_f32_16x16x32_bf16 v[112:115], v[52:55], v[44:47], v[112:115]
	v_mfma_f32_16x16x32_bf16 v[116:119], v[60:63], v[44:47], v[116:119]
	s_waitcnt vmcnt(6)
	s_barrier
	s_add_i32 m0, s32, 0
	s_nop 0
	global_load_lds_dwordx4 v64, s[4:5]
	s_add_i32 m0, s33, 0
	s_nop 0
	global_load_lds_dwordx4 v65, s[6:7]
	s_add_i32 m0, s33, 1024
	s_nop 0
	global_load_lds_dwordx4 v66, s[6:7]
	s_add_u32 s4, s4, 0x80
	s_addc_u32 s5, s5, 0
	s_add_u32 s6, s6, 0x80
	s_addc_u32 s7, s7, 0
	ds_read_b128 v[48:51], v68 offset:24576
	ds_read_b128 v[56:59], v68 offset:26624
	ds_read_b128 v[32:35], v67 offset:24576
	ds_read_b128 v[40:43], v67 offset:26624
	ds_read_b128 v[52:55], v68 offset:25600
	ds_read_b128 v[60:63], v68 offset:27648
	ds_read_b128 v[36:39], v67 offset:25600
	ds_read_b128 v[44:47], v67 offset:27648
	s_waitcnt lgkmcnt(4)
	v_mfma_f32_16x16x32_bf16 v[104:107], v[48:51], v[32:35], v[104:107]
	v_mfma_f32_16x16x32_bf16 v[108:111], v[56:59], v[32:35], v[108:111]
	v_mfma_f32_16x16x32_bf16 v[112:115], v[48:51], v[40:43], v[112:115]
	v_mfma_f32_16x16x32_bf16 v[116:119], v[56:59], v[40:43], v[116:119]
	s_waitcnt lgkmcnt(0)
	v_mfma_f32_16x16x32_bf16 v[104:107], v[52:55], v[36:39], v[104:107]
	v_mfma_f32_16x16x32_bf16 v[108:111], v[60:63], v[36:39], v[108:111]
	v_mfma_f32_16x16x32_bf16 v[112:115], v[52:55], v[44:47], v[112:115]
	v_mfma_f32_16x16x32_bf16 v[116:119], v[60:63], v[44:47], v[116:119]
	s_waitcnt vmcnt(6)
	s_barrier
	s_add_i32 m0, s32, 24576
	s_nop 0
	global_load_lds_dwordx4 v64, s[4:5]
	s_add_i32 m0, s33, 24576
	s_nop 0
	global_load_lds_dwordx4 v65, s[6:7]
	s_add_i32 m0, s33, 25600
	s_nop 0
	global_load_lds_dwordx4 v66, s[6:7]
	s_add_u32 s4, s4, 0x80
	s_addc_u32 s5, s5, 0
	s_add_u32 s6, s6, 0x80
	s_addc_u32 s7, s7, 0
	ds_read_b128 v[48:51], v70 offset:0
	ds_read_b128 v[56:59], v70 offset:2048
	ds_read_b128 v[32:35], v69 offset:0
	ds_read_b128 v[40:43], v69 offset:2048
	ds_read_b128 v[52:55], v70 offset:1024
	ds_read_b128 v[60:63], v70 offset:3072
	ds_read_b128 v[36:39], v69 offset:1024
	ds_read_b128 v[44:47], v69 offset:3072
	s_waitcnt lgkmcnt(4)
	v_mfma_f32_16x16x32_bf16 v[104:107], v[48:51], v[32:35], v[104:107]
	v_mfma_f32_16x16x32_bf16 v[108:111], v[56:59], v[32:35], v[108:111]
	v_mfma_f32_16x16x32_bf16 v[112:115], v[48:51], v[40:43], v[112:115]
	v_mfma_f32_16x16x32_bf16 v[116:119], v[56:59], v[40:43], v[116:119]
	s_waitcnt lgkmcnt(0)
	v_mfma_f32_16x16x32_bf16 v[104:107], v[52:55], v[36:39], v[104:107]
	v_mfma_f32_16x16x32_bf16 v[108:111], v[60:63], v[36:39], v[108:111]
	v_mfma_f32_16x16x32_bf16 v[112:115], v[52:55], v[44:47], v[112:115]
	v_mfma_f32_16x16x32_bf16 v[116:119], v[60:63], v[44:47], v[116:119]
	s_waitcnt vmcnt(6)
	s_barrier
	s_add_i32 m0, s32, 49152
	s_nop 0
	global_load_lds_dwordx4 v64, s[4:5]
	s_add_i32 m0, s33, 49152
	s_nop 0
	global_load_lds_dwordx4 v65, s[6:7]
	s_add_i32 m0, s33, 50176
	s_nop 0
	global_load_lds_dwordx4 v66, s[6:7]
	s_add_u32 s4, s4, 0x80
	s_addc_u32 s5, s5, 0
	s_add_u32 s6, s6, 0x80
	s_addc_u32 s7, s7, 0
	ds_read_b128 v[48:51], v70 offset:24576
	ds_read_b128 v[56:59], v70 offset:26624
	ds_read_b128 v[32:35], v69 offset:24576
	ds_read_b128 v[40:43], v69 offset:26624
	ds_read_b128 v[52:55], v70 offset:25600
	ds_read_b128 v[60:63], v70 offset:27648
	ds_read_b128 v[36:39], v69 offset:25600
	ds_read_b128 v[44:47], v69 offset:27648
	s_waitcnt lgkmcnt(4)
	v_mfma_f32_16x16x32_bf16 v[104:107], v[48:51], v[32:35], v[104:107]
	v_mfma_f32_16x16x32_bf16 v[108:111], v[56:59], v[32:35], v[108:111]
	v_mfma_f32_16x16x32_bf16 v[112:115], v[48:51], v[40:43], v[112:115]
	v_mfma_f32_16x16x32_bf16 v[116:119], v[56:59], v[40:43], v[116:119]
	s_waitcnt lgkmcnt(0)
	v_mfma_f32_16x16x32_bf16 v[104:107], v[52:55], v[36:39], v[104:107]
	v_mfma_f32_16x16x32_bf16 v[108:111], v[60:63], v[36:39], v[108:111]
	v_mfma_f32_16x16x32_bf16 v[112:115], v[52:55], v[44:47], v[112:115]
	v_mfma_f32_16x16x32_bf16 v[116:119], v[60:63], v[44:47], v[116:119]
	s_waitcnt vmcnt(6)
	s_barrier
	s_add_i32 m0, s32, 73728
	s_nop 0
	global_load_lds_dwordx4 v64, s[4:5]
	s_add_i32 m0, s33, 73728
	s_nop 0
	global_load_lds_dwordx4 v65, s[6:7]
	s_add_i32 m0, s33, 74752
	s_nop 0
	global_load_lds_dwordx4 v66, s[6:7]
	s_add_u32 s4, s4, 0x80
	s_addc_u32 s5, s5, 0
	s_add_u32 s6, s6, 0x80
	s_addc_u32 s7, s7, 0
	ds_read_b128 v[48:51], v68 offset:0
	ds_read_b128 v[56:59], v68 offset:2048
	ds_read_b128 v[32:35], v67 offset:0
	ds_read_b128 v[40:43], v67 offset:2048
	ds_read_b128 v[52:55], v68 offset:1024
	ds_read_b128 v[60:63], v68 offset:3072
	ds_read_b128 v[36:39], v67 offset:1024
	ds_read_b128 v[44:47], v67 offset:3072
	s_waitcnt lgkmcnt(4)
	v_mfma_f32_16x16x32_bf16 v[120:123], v[48:51], v[32:35], v[120:123]
	v_mfma_f32_16x16x32_bf16 v[124:127], v[56:59], v[32:35], v[124:127]
	v_mfma_f32_16x16x32_bf16 v[128:131], v[48:51], v[40:43], v[128:131]
	v_mfma_f32_16x16x32_bf16 v[132:135], v[56:59], v[40:43], v[132:135]
	s_waitcnt lgkmcnt(0)
	v_mfma_f32_16x16x32_bf16 v[120:123], v[52:55], v[36:39], v[120:123]
	v_mfma_f32_16x16x32_bf16 v[124:127], v[60:63], v[36:39], v[124:127]
	v_mfma_f32_16x16x32_bf16 v[128:131], v[52:55], v[44:47], v[128:131]
	v_mfma_f32_16x16x32_bf16 v[132:135], v[60:63], v[44:47], v[132:135]
	s_waitcnt vmcnt(6)
	s_barrier
	s_add_i32 m0, s32, 0
	s_nop 0
	global_load_lds_dwordx4 v64, s[4:5]
	s_add_i32 m0, s33, 0
	s_nop 0
	global_load_lds_dwordx4 v65, s[6:7]
	s_add_i32 m0, s33, 1024
	s_nop 0
	global_load_lds_dwordx4 v66, s[6:7]
	s_add_u32 s4, s4, 0x80
	s_addc_u32 s5, s5, 0
	s_add_u32 s6, s6, 0x80
	s_addc_u32 s7, s7, 0
	ds_read_b128 v[48:51], v68 offset:24576
	ds_read_b128 v[56:59], v68 offset:26624
	ds_read_b128 v[32:35], v67 offset:24576
	ds_read_b128 v[40:43], v67 offset:26624
	ds_read_b128 v[52:55], v68 offset:25600
	ds_read_b128 v[60:63], v68 offset:27648
	ds_read_b128 v[36:39], v67 offset:25600
	ds_read_b128 v[44:47], v67 offset:27648
	s_waitcnt lgkmcnt(4)
	v_mfma_f32_16x16x32_bf16 v[120:123], v[48:51], v[32:35], v[120:123]
	v_mfma_f32_16x16x32_bf16 v[124:127], v[56:59], v[32:35], v[124:127]
	v_mfma_f32_16x16x32_bf16 v[128:131], v[48:51], v[40:43], v[128:131]
	v_mfma_f32_16x16x32_bf16 v[132:135], v[56:59], v[40:43], v[132:135]
	s_waitcnt lgkmcnt(0)
	v_mfma_f32_16x16x32_bf16 v[120:123], v[52:55], v[36:39], v[120:123]
	v_mfma_f32_16x16x32_bf16 v[124:127], v[60:63], v[36:39], v[124:127]
	v_mfma_f32_16x16x32_bf16 v[128:131], v[52:55], v[44:47], v[128:131]
	v_mfma_f32_16x16x32_bf16 v[132:135], v[60:63], v[44:47], v[132:135]
	s_waitcnt vmcnt(6)
	s_barrier
	s_add_i32 m0, s32, 24576
	s_nop 0
	global_load_lds_dwordx4 v64, s[4:5]
	s_add_i32 m0, s33, 24576
	s_nop 0
	global_load_lds_dwordx4 v65, s[6:7]
	s_add_i32 m0, s33, 25600
	s_nop 0
	global_load_lds_dwordx4 v66, s[6:7]
	s_add_u32 s4, s4, 0x80
	s_addc_u32 s5, s5, 0
	s_add_u32 s6, s6, 0x80
	s_addc_u32 s7, s7, 0
	ds_read_b128 v[48:51], v70 offset:0
	ds_read_b128 v[56:59], v70 offset:2048
	ds_read_b128 v[32:35], v69 offset:0
	ds_read_b128 v[40:43], v69 offset:2048
	ds_read_b128 v[52:55], v70 offset:1024
	ds_read_b128 v[60:63], v70 offset:3072
	ds_read_b128 v[36:39], v69 offset:1024
	ds_read_b128 v[44:47], v69 offset:3072
	s_waitcnt lgkmcnt(4)
	v_mfma_f32_16x16x32_bf16 v[120:123], v[48:51], v[32:35], v[120:123]
	v_mfma_f32_16x16x32_bf16 v[124:127], v[56:59], v[32:35], v[124:127]
	v_mfma_f32_16x16x32_bf16 v[128:131], v[48:51], v[40:43], v[128:131]
	v_mfma_f32_16x16x32_bf16 v[132:135], v[56:59], v[40:43], v[132:135]
	s_waitcnt lgkmcnt(0)
	v_mfma_f32_16x16x32_bf16 v[120:123], v[52:55], v[36:39], v[120:123]
	v_mfma_f32_16x16x32_bf16 v[124:127], v[60:63], v[36:39], v[124:127]
	v_mfma_f32_16x16x32_bf16 v[128:131], v[52:55], v[44:47], v[128:131]
	v_mfma_f32_16x16x32_bf16 v[132:135], v[60:63], v[44:47], v[132:135]
	s_waitcnt vmcnt(6)
	s_barrier
	s_add_i32 m0, s32, 49152
	s_nop 0
	global_load_lds_dwordx4 v64, s[4:5]
	s_add_i32 m0, s33, 49152
	s_nop 0
	global_load_lds_dwordx4 v65, s[6:7]
	s_add_i32 m0, s33, 50176
	s_nop 0
	global_load_lds_dwordx4 v66, s[6:7]
	s_add_u32 s4, s4, 0x80
	s_addc_u32 s5, s5, 0
	s_add_u32 s6, s6, 0x80
	s_addc_u32 s7, s7, 0
	ds_read_b128 v[48:51], v70 offset:24576
	ds_read_b128 v[56:59], v70 offset:26624
	ds_read_b128 v[32:35], v69 offset:24576
	ds_read_b128 v[40:43], v69 offset:26624
	ds_read_b128 v[52:55], v70 offset:25600
	ds_read_b128 v[60:63], v70 offset:27648
	ds_read_b128 v[36:39], v69 offset:25600
	ds_read_b128 v[44:47], v69 offset:27648
	s_waitcnt lgkmcnt(4)
	v_mfma_f32_16x16x32_bf16 v[120:123], v[48:51], v[32:35], v[120:123]
	v_mfma_f32_16x16x32_bf16 v[124:127], v[56:59], v[32:35], v[124:127]
	v_mfma_f32_16x16x32_bf16 v[128:131], v[48:51], v[40:43], v[128:131]
	v_mfma_f32_16x16x32_bf16 v[132:135], v[56:59], v[40:43], v[132:135]
	s_waitcnt lgkmcnt(0)
	v_mfma_f32_16x16x32_bf16 v[120:123], v[52:55], v[36:39], v[120:123]
	v_mfma_f32_16x16x32_bf16 v[124:127], v[60:63], v[36:39], v[124:127]
	v_mfma_f32_16x16x32_bf16 v[128:131], v[52:55], v[44:47], v[128:131]
	v_mfma_f32_16x16x32_bf16 v[132:135], v[60:63], v[44:47], v[132:135]
	s_waitcnt vmcnt(6)
	s_barrier
	s_add_i32 m0, s32, 73728
	s_nop 0
	global_load_lds_dwordx4 v64, s[4:5]
	s_add_i32 m0, s33, 73728
	s_nop 0
	global_load_lds_dwordx4 v65, s[6:7]
	s_add_i32 m0, s33, 74752
	s_nop 0
	global_load_lds_dwordx4 v66, s[6:7]
	s_add_u32 s4, s4, 0x80
	s_addc_u32 s5, s5, 0
	s_add_u32 s6, s6, 0x80
	s_addc_u32 s7, s7, 0
	ds_read_b128 v[48:51], v68 offset:0
	ds_read_b128 v[56:59], v68 offset:2048
	ds_read_b128 v[32:35], v67 offset:0
	ds_read_b128 v[40:43], v67 offset:2048
	ds_read_b128 v[52:55], v68 offset:1024
	ds_read_b128 v[60:63], v68 offset:3072
	ds_read_b128 v[36:39], v67 offset:1024
	ds_read_b128 v[44:47], v67 offset:3072
	s_waitcnt lgkmcnt(4)
	v_mfma_f32_16x16x32_bf16 v[136:139], v[48:51], v[32:35], v[136:139]
	v_mfma_f32_16x16x32_bf16 v[140:143], v[56:59], v[32:35], v[140:143]
	v_mfma_f32_16x16x32_bf16 v[144:147], v[48:51], v[40:43], v[144:147]
	v_mfma_f32_16x16x32_bf16 v[148:151], v[56:59], v[40:43], v[148:151]
	s_waitcnt lgkmcnt(0)
	v_mfma_f32_16x16x32_bf16 v[136:139], v[52:55], v[36:39], v[136:139]
	v_mfma_f32_16x16x32_bf16 v[140:143], v[60:63], v[36:39], v[140:143]
	v_mfma_f32_16x16x32_bf16 v[144:147], v[52:55], v[44:47], v[144:147]
	v_mfma_f32_16x16x32_bf16 v[148:151], v[60:63], v[44:47], v[148:151]
	s_waitcnt vmcnt(6)
	s_barrier
	ds_read_b128 v[48:51], v68 offset:24576
	ds_read_b128 v[56:59], v68 offset:26624
	ds_read_b128 v[32:35], v67 offset:24576
	ds_read_b128 v[40:43], v67 offset:26624
	ds_read_b128 v[52:55], v68 offset:25600
	ds_read_b128 v[60:63], v68 offset:27648
	ds_read_b128 v[36:39], v67 offset:25600
	ds_read_b128 v[44:47], v67 offset:27648
	s_waitcnt lgkmcnt(4)
	v_mfma_f32_16x16x32_bf16 v[136:139], v[48:51], v[32:35], v[136:139]
	v_mfma_f32_16x16x32_bf16 v[140:143], v[56:59], v[32:35], v[140:143]
	v_mfma_f32_16x16x32_bf16 v[144:147], v[48:51], v[40:43], v[144:147]
	v_mfma_f32_16x16x32_bf16 v[148:151], v[56:59], v[40:43], v[148:151]
	s_waitcnt lgkmcnt(0)
	v_mfma_f32_16x16x32_bf16 v[136:139], v[52:55], v[36:39], v[136:139]
	v_mfma_f32_16x16x32_bf16 v[140:143], v[60:63], v[36:39], v[140:143]
	v_mfma_f32_16x16x32_bf16 v[144:147], v[52:55], v[44:47], v[144:147]
	v_mfma_f32_16x16x32_bf16 v[148:151], v[60:63], v[44:47], v[148:151]
	s_waitcnt vmcnt(3)
	s_barrier
	ds_read_b128 v[48:51], v70 offset:0
	ds_read_b128 v[56:59], v70 offset:2048
	ds_read_b128 v[32:35], v69 offset:0
	ds_read_b128 v[40:43], v69 offset:2048
	ds_read_b128 v[52:55], v70 offset:1024
	ds_read_b128 v[60:63], v70 offset:3072
	ds_read_b128 v[36:39], v69 offset:1024
	ds_read_b128 v[44:47], v69 offset:3072
	s_waitcnt lgkmcnt(4)
	v_mfma_f32_16x16x32_bf16 v[136:139], v[48:51], v[32:35], v[136:139]
	v_mfma_f32_16x16x32_bf16 v[140:143], v[56:59], v[32:35], v[140:143]
	v_mfma_f32_16x16x32_bf16 v[144:147], v[48:51], v[40:43], v[144:147]
	v_mfma_f32_16x16x32_bf16 v[148:151], v[56:59], v[40:43], v[148:151]
	s_waitcnt lgkmcnt(0)
	v_mfma_f32_16x16x32_bf16 v[136:139], v[52:55], v[36:39], v[136:139]
	v_mfma_f32_16x16x32_bf16 v[140:143], v[60:63], v[36:39], v[140:143]
	v_mfma_f32_16x16x32_bf16 v[144:147], v[52:55], v[44:47], v[144:147]
	v_mfma_f32_16x16x32_bf16 v[148:151], v[60:63], v[44:47], v[148:151]
	s_waitcnt vmcnt(0)
	s_barrier
	ds_read_b128 v[48:51], v70 offset:24576
	ds_read_b128 v[56:59], v70 offset:26624
	ds_read_b128 v[32:35], v69 offset:24576
	ds_read_b128 v[40:43], v69 offset:26624
	ds_read_b128 v[52:55], v70 offset:25600
	ds_read_b128 v[60:63], v70 offset:27648
	ds_read_b128 v[36:39], v69 offset:25600
	ds_read_b128 v[44:47], v69 offset:27648
	s_waitcnt lgkmcnt(4)
	v_mfma_f32_16x16x32_bf16 v[136:139], v[48:51], v[32:35], v[136:139]
	v_mfma_f32_16x16x32_bf16 v[140:143], v[56:59], v[32:35], v[140:143]
	v_mfma_f32_16x16x32_bf16 v[144:147], v[48:51], v[40:43], v[144:147]
	v_mfma_f32_16x16x32_bf16 v[148:151], v[56:59], v[40:43], v[148:151]
	s_waitcnt lgkmcnt(0)
	v_mfma_f32_16x16x32_bf16 v[136:139], v[52:55], v[36:39], v[136:139]
	v_mfma_f32_16x16x32_bf16 v[140:143], v[60:63], v[36:39], v[140:143]
	v_mfma_f32_16x16x32_bf16 v[144:147], v[52:55], v[44:47], v[144:147]
	v_mfma_f32_16x16x32_bf16 v[148:151], v[60:63], v[44:47], v[148:151]
	s_nop 7
	s_nop 1
	v_lshlrev_b32_e32 v48, 16, v168
	v_and_b32_e32 v49, 0xffff0000, v168
	v_lshlrev_b32_e32 v50, 16, v169
	v_and_b32_e32 v51, 0xffff0000, v169
	v_lshlrev_b32_e32 v52, 16, v176
	v_and_b32_e32 v53, 0xffff0000, v176
	v_lshlrev_b32_e32 v54, 16, v177
	v_and_b32_e32 v55, 0xffff0000, v177
	v_lshlrev_b32_e32 v56, 16, v184
	v_and_b32_e32 v57, 0xffff0000, v184
	v_lshlrev_b32_e32 v58, 16, v185
	v_and_b32_e32 v59, 0xffff0000, v185
	v_lshlrev_b32_e32 v60, 16, v192
	v_and_b32_e32 v61, 0xffff0000, v192
	v_lshlrev_b32_e32 v62, 16, v193
	v_and_b32_e32 v63, 0xffff0000, v193
	v_add_f32_e32 v48, v48, v72
	v_add_f32_e32 v49, v49, v73
	v_add_f32_e32 v50, v50, v74
	v_add_f32_e32 v51, v51, v75
	v_add_f32_e32 v52, v52, v80
	v_add_f32_e32 v53, v53, v81
	v_add_f32_e32 v54, v54, v82
	v_add_f32_e32 v55, v55, v83
	v_add_f32_e32 v56, v56, v88
	v_add_f32_e32 v57, v57, v89
	v_add_f32_e32 v58, v58, v90
	v_add_f32_e32 v59, v59, v91
	v_add_f32_e32 v60, v60, v96
	v_add_f32_e32 v61, v61, v97
	v_add_f32_e32 v62, v62, v98
	v_add_f32_e32 v63, v63, v99
	v_mul_f32_e32 v48, 0xbfb8aa3b, v48
	v_mul_f32_e32 v49, 0xbfb8aa3b, v49
	v_mul_f32_e32 v50, 0xbfb8aa3b, v50
	v_mul_f32_e32 v51, 0xbfb8aa3b, v51
	v_mul_f32_e32 v52, 0xbfb8aa3b, v52
	v_mul_f32_e32 v53, 0xbfb8aa3b, v53
	v_mul_f32_e32 v54, 0xbfb8aa3b, v54
	v_mul_f32_e32 v55, 0xbfb8aa3b, v55
	v_mul_f32_e32 v56, 0xbfb8aa3b, v56
	v_mul_f32_e32 v57, 0xbfb8aa3b, v57
	v_mul_f32_e32 v58, 0xbfb8aa3b, v58
	v_mul_f32_e32 v59, 0xbfb8aa3b, v59
	v_mul_f32_e32 v60, 0xbfb8aa3b, v60
	v_mul_f32_e32 v61, 0xbfb8aa3b, v61
	v_mul_f32_e32 v62, 0xbfb8aa3b, v62
	v_mul_f32_e32 v63, 0xbfb8aa3b, v63
	v_exp_f32_e32 v48, v48
	v_exp_f32_e32 v49, v49
	v_exp_f32_e32 v50, v50
	v_exp_f32_e32 v51, v51
	v_exp_f32_e32 v52, v52
	v_exp_f32_e32 v53, v53
	v_exp_f32_e32 v54, v54
	v_exp_f32_e32 v55, v55
	v_exp_f32_e32 v56, v56
	v_exp_f32_e32 v57, v57
	v_exp_f32_e32 v58, v58
	v_exp_f32_e32 v59, v59
	v_exp_f32_e32 v60, v60
	v_exp_f32_e32 v61, v61
	v_exp_f32_e32 v62, v62
	v_exp_f32_e32 v63, v63
	v_min_f32_e32 v48, 0x60ad78ec, v48
	v_min_f32_e32 v49, 0x60ad78ec, v49
	v_min_f32_e32 v50, 0x60ad78ec, v50
	v_min_f32_e32 v51, 0x60ad78ec, v51
	v_min_f32_e32 v52, 0x60ad78ec, v52
	v_min_f32_e32 v53, 0x60ad78ec, v53
	v_min_f32_e32 v54, 0x60ad78ec, v54
	v_min_f32_e32 v55, 0x60ad78ec, v55
	v_min_f32_e32 v56, 0x60ad78ec, v56
	v_min_f32_e32 v57, 0x60ad78ec, v57
	v_min_f32_e32 v58, 0x60ad78ec, v58
	v_min_f32_e32 v59, 0x60ad78ec, v59
	v_min_f32_e32 v60, 0x60ad78ec, v60
	v_min_f32_e32 v61, 0x60ad78ec, v61
	v_min_f32_e32 v62, 0x60ad78ec, v62
	v_min_f32_e32 v63, 0x60ad78ec, v63
	v_add_f32_e32 v48, 1.0, v48
	v_add_f32_e32 v49, 1.0, v49
	v_add_f32_e32 v50, 1.0, v50
	v_add_f32_e32 v51, 1.0, v51
	v_add_f32_e32 v52, 1.0, v52
	v_add_f32_e32 v53, 1.0, v53
	v_add_f32_e32 v54, 1.0, v54
	v_add_f32_e32 v55, 1.0, v55
	v_add_f32_e32 v56, 1.0, v56
	v_add_f32_e32 v57, 1.0, v57
	v_add_f32_e32 v58, 1.0, v58
	v_add_f32_e32 v59, 1.0, v59
	v_add_f32_e32 v60, 1.0, v60
	v_add_f32_e32 v61, 1.0, v61
	v_add_f32_e32 v62, 1.0, v62
	v_add_f32_e32 v63, 1.0, v63
	v_rcp_f32_e32 v48, v48
	v_rcp_f32_e32 v49, v49
	v_rcp_f32_e32 v50, v50
	v_rcp_f32_e32 v51, v51
	v_rcp_f32_e32 v52, v52
	v_rcp_f32_e32 v53, v53
	v_rcp_f32_e32 v54, v54
	v_rcp_f32_e32 v55, v55
	v_rcp_f32_e32 v56, v56
	v_rcp_f32_e32 v57, v57
	v_rcp_f32_e32 v58, v58
	v_rcp_f32_e32 v59, v59
	v_rcp_f32_e32 v60, v60
	v_rcp_f32_e32 v61, v61
	v_rcp_f32_e32 v62, v62
	v_rcp_f32_e32 v63, v63
	v_mul_f32_e32 v32, v48, v16
	v_mul_f32_e32 v33, v49, v17
	v_mul_f32_e32 v34, v50, v18
	v_mul_f32_e32 v35, v51, v19
	v_fmac_f32_e32 v32, v52, v104
	v_fmac_f32_e32 v33, v53, v105
	v_fmac_f32_e32 v34, v54, v106
	v_fmac_f32_e32 v35, v55, v107
	v_fmac_f32_e32 v32, v56, v120
	v_fmac_f32_e32 v33, v57, v121
	v_fmac_f32_e32 v34, v58, v122
	v_fmac_f32_e32 v35, v59, v123
	v_fmac_f32_e32 v32, v60, v136
	v_fmac_f32_e32 v33, v61, v137
	v_fmac_f32_e32 v34, v62, v138
	v_fmac_f32_e32 v35, v63, v139
	v_lshlrev_b32_e32 v48, 16, v170
	v_and_b32_e32 v49, 0xffff0000, v170
	v_lshlrev_b32_e32 v50, 16, v171
	v_and_b32_e32 v51, 0xffff0000, v171
	v_lshlrev_b32_e32 v52, 16, v178
	v_and_b32_e32 v53, 0xffff0000, v178
	v_lshlrev_b32_e32 v54, 16, v179
	v_and_b32_e32 v55, 0xffff0000, v179
	v_lshlrev_b32_e32 v56, 16, v186
	v_and_b32_e32 v57, 0xffff0000, v186
	v_lshlrev_b32_e32 v58, 16, v187
	v_and_b32_e32 v59, 0xffff0000, v187
	v_lshlrev_b32_e32 v60, 16, v194
	v_and_b32_e32 v61, 0xffff0000, v194
	v_lshlrev_b32_e32 v62, 16, v195
	v_and_b32_e32 v63, 0xffff0000, v195
	v_add_f32_e32 v48, v48, v76
	v_add_f32_e32 v49, v49, v77
	v_add_f32_e32 v50, v50, v78
	v_add_f32_e32 v51, v51, v79
	v_add_f32_e32 v52, v52, v84
	v_add_f32_e32 v53, v53, v85
	v_add_f32_e32 v54, v54, v86
	v_add_f32_e32 v55, v55, v87
	v_add_f32_e32 v56, v56, v92
	v_add_f32_e32 v57, v57, v93
	v_add_f32_e32 v58, v58, v94
	v_add_f32_e32 v59, v59, v95
	v_add_f32_e32 v60, v60, v100
	v_add_f32_e32 v61, v61, v101
	v_add_f32_e32 v62, v62, v102
	v_add_f32_e32 v63, v63, v103
	v_mul_f32_e32 v48, 0xbfb8aa3b, v48
	v_mul_f32_e32 v49, 0xbfb8aa3b, v49
	v_mul_f32_e32 v50, 0xbfb8aa3b, v50
	v_mul_f32_e32 v51, 0xbfb8aa3b, v51
	v_mul_f32_e32 v52, 0xbfb8aa3b, v52
	v_mul_f32_e32 v53, 0xbfb8aa3b, v53
	v_mul_f32_e32 v54, 0xbfb8aa3b, v54
	v_mul_f32_e32 v55, 0xbfb8aa3b, v55
	v_mul_f32_e32 v56, 0xbfb8aa3b, v56
	v_mul_f32_e32 v57, 0xbfb8aa3b, v57
	v_mul_f32_e32 v58, 0xbfb8aa3b, v58
	v_mul_f32_e32 v59, 0xbfb8aa3b, v59
	v_mul_f32_e32 v60, 0xbfb8aa3b, v60
	v_mul_f32_e32 v61, 0xbfb8aa3b, v61
	v_mul_f32_e32 v62, 0xbfb8aa3b, v62
	v_mul_f32_e32 v63, 0xbfb8aa3b, v63
	v_exp_f32_e32 v48, v48
	v_exp_f32_e32 v49, v49
	v_exp_f32_e32 v50, v50
	v_exp_f32_e32 v51, v51
	v_exp_f32_e32 v52, v52
	v_exp_f32_e32 v53, v53
	v_exp_f32_e32 v54, v54
	v_exp_f32_e32 v55, v55
	v_exp_f32_e32 v56, v56
	v_exp_f32_e32 v57, v57
	v_exp_f32_e32 v58, v58
	v_exp_f32_e32 v59, v59
	v_exp_f32_e32 v60, v60
	v_exp_f32_e32 v61, v61
	v_exp_f32_e32 v62, v62
	v_exp_f32_e32 v63, v63
	v_min_f32_e32 v48, 0x60ad78ec, v48
	v_min_f32_e32 v49, 0x60ad78ec, v49
	v_min_f32_e32 v50, 0x60ad78ec, v50
	v_min_f32_e32 v51, 0x60ad78ec, v51
	v_min_f32_e32 v52, 0x60ad78ec, v52
	v_min_f32_e32 v53, 0x60ad78ec, v53
	v_min_f32_e32 v54, 0x60ad78ec, v54
	v_min_f32_e32 v55, 0x60ad78ec, v55
	v_min_f32_e32 v56, 0x60ad78ec, v56
	v_min_f32_e32 v57, 0x60ad78ec, v57
	v_min_f32_e32 v58, 0x60ad78ec, v58
	v_min_f32_e32 v59, 0x60ad78ec, v59
	v_min_f32_e32 v60, 0x60ad78ec, v60
	v_min_f32_e32 v61, 0x60ad78ec, v61
	v_min_f32_e32 v62, 0x60ad78ec, v62
	v_min_f32_e32 v63, 0x60ad78ec, v63
	v_add_f32_e32 v48, 1.0, v48
	v_add_f32_e32 v49, 1.0, v49
	v_add_f32_e32 v50, 1.0, v50
	v_add_f32_e32 v51, 1.0, v51
	v_add_f32_e32 v52, 1.0, v52
	v_add_f32_e32 v53, 1.0, v53
	v_add_f32_e32 v54, 1.0, v54
	v_add_f32_e32 v55, 1.0, v55
	v_add_f32_e32 v56, 1.0, v56
	v_add_f32_e32 v57, 1.0, v57
	v_add_f32_e32 v58, 1.0, v58
	v_add_f32_e32 v59, 1.0, v59
	v_add_f32_e32 v60, 1.0, v60
	v_add_f32_e32 v61, 1.0, v61
	v_add_f32_e32 v62, 1.0, v62
	v_add_f32_e32 v63, 1.0, v63
	v_rcp_f32_e32 v48, v48
	v_rcp_f32_e32 v49, v49
	v_rcp_f32_e32 v50, v50
	v_rcp_f32_e32 v51, v51
	v_rcp_f32_e32 v52, v52
	v_rcp_f32_e32 v53, v53
	v_rcp_f32_e32 v54, v54
	v_rcp_f32_e32 v55, v55
	v_rcp_f32_e32 v56, v56
	v_rcp_f32_e32 v57, v57
	v_rcp_f32_e32 v58, v58
	v_rcp_f32_e32 v59, v59
	v_rcp_f32_e32 v60, v60
	v_rcp_f32_e32 v61, v61
	v_rcp_f32_e32 v62, v62
	v_rcp_f32_e32 v63, v63
	v_mul_f32_e32 v36, v48, v20
	v_mul_f32_e32 v37, v49, v21
	v_mul_f32_e32 v38, v50, v22
	v_mul_f32_e32 v39, v51, v23
	v_fmac_f32_e32 v36, v52, v108
	v_fmac_f32_e32 v37, v53, v109
	v_fmac_f32_e32 v38, v54, v110
	v_fmac_f32_e32 v39, v55, v111
	v_fmac_f32_e32 v36, v56, v124
	v_fmac_f32_e32 v37, v57, v125
	v_fmac_f32_e32 v38, v58, v126
	v_fmac_f32_e32 v39, v59, v127
	v_fmac_f32_e32 v36, v60, v140
	v_fmac_f32_e32 v37, v61, v141
	v_fmac_f32_e32 v38, v62, v142
	v_fmac_f32_e32 v39, v63, v143
	v_lshlrev_b32_e32 v48, 16, v172
	v_and_b32_e32 v49, 0xffff0000, v172
	v_lshlrev_b32_e32 v50, 16, v173
	v_and_b32_e32 v51, 0xffff0000, v173
	v_lshlrev_b32_e32 v52, 16, v180
	v_and_b32_e32 v53, 0xffff0000, v180
	v_lshlrev_b32_e32 v54, 16, v181
	v_and_b32_e32 v55, 0xffff0000, v181
	v_lshlrev_b32_e32 v56, 16, v188
	v_and_b32_e32 v57, 0xffff0000, v188
	v_lshlrev_b32_e32 v58, 16, v189
	v_and_b32_e32 v59, 0xffff0000, v189
	v_lshlrev_b32_e32 v60, 16, v196
	v_and_b32_e32 v61, 0xffff0000, v196
	v_lshlrev_b32_e32 v62, 16, v197
	v_and_b32_e32 v63, 0xffff0000, v197
	v_add_f32_e32 v48, v48, v72
	v_add_f32_e32 v49, v49, v73
	v_add_f32_e32 v50, v50, v74
	v_add_f32_e32 v51, v51, v75
	v_add_f32_e32 v52, v52, v80
	v_add_f32_e32 v53, v53, v81
	v_add_f32_e32 v54, v54, v82
	v_add_f32_e32 v55, v55, v83
	v_add_f32_e32 v56, v56, v88
	v_add_f32_e32 v57, v57, v89
	v_add_f32_e32 v58, v58, v90
	v_add_f32_e32 v59, v59, v91
	v_add_f32_e32 v60, v60, v96
	v_add_f32_e32 v61, v61, v97
	v_add_f32_e32 v62, v62, v98
	v_add_f32_e32 v63, v63, v99
	v_mul_f32_e32 v48, 0xbfb8aa3b, v48
	v_mul_f32_e32 v49, 0xbfb8aa3b, v49
	v_mul_f32_e32 v50, 0xbfb8aa3b, v50
	v_mul_f32_e32 v51, 0xbfb8aa3b, v51
	v_mul_f32_e32 v52, 0xbfb8aa3b, v52
	v_mul_f32_e32 v53, 0xbfb8aa3b, v53
	v_mul_f32_e32 v54, 0xbfb8aa3b, v54
	v_mul_f32_e32 v55, 0xbfb8aa3b, v55
	v_mul_f32_e32 v56, 0xbfb8aa3b, v56
	v_mul_f32_e32 v57, 0xbfb8aa3b, v57
	v_mul_f32_e32 v58, 0xbfb8aa3b, v58
	v_mul_f32_e32 v59, 0xbfb8aa3b, v59
	v_mul_f32_e32 v60, 0xbfb8aa3b, v60
	v_mul_f32_e32 v61, 0xbfb8aa3b, v61
	v_mul_f32_e32 v62, 0xbfb8aa3b, v62
	v_mul_f32_e32 v63, 0xbfb8aa3b, v63
	v_exp_f32_e32 v48, v48
	v_exp_f32_e32 v49, v49
	v_exp_f32_e32 v50, v50
	v_exp_f32_e32 v51, v51
	v_exp_f32_e32 v52, v52
	v_exp_f32_e32 v53, v53
	v_exp_f32_e32 v54, v54
	v_exp_f32_e32 v55, v55
	v_exp_f32_e32 v56, v56
	v_exp_f32_e32 v57, v57
	v_exp_f32_e32 v58, v58
	v_exp_f32_e32 v59, v59
	v_exp_f32_e32 v60, v60
	v_exp_f32_e32 v61, v61
	v_exp_f32_e32 v62, v62
	v_exp_f32_e32 v63, v63
	v_min_f32_e32 v48, 0x60ad78ec, v48
	v_min_f32_e32 v49, 0x60ad78ec, v49
	v_min_f32_e32 v50, 0x60ad78ec, v50
	v_min_f32_e32 v51, 0x60ad78ec, v51
	v_min_f32_e32 v52, 0x60ad78ec, v52
	v_min_f32_e32 v53, 0x60ad78ec, v53
	v_min_f32_e32 v54, 0x60ad78ec, v54
	v_min_f32_e32 v55, 0x60ad78ec, v55
	v_min_f32_e32 v56, 0x60ad78ec, v56
	v_min_f32_e32 v57, 0x60ad78ec, v57
	v_min_f32_e32 v58, 0x60ad78ec, v58
	v_min_f32_e32 v59, 0x60ad78ec, v59
	v_min_f32_e32 v60, 0x60ad78ec, v60
	v_min_f32_e32 v61, 0x60ad78ec, v61
	v_min_f32_e32 v62, 0x60ad78ec, v62
	v_min_f32_e32 v63, 0x60ad78ec, v63
	v_add_f32_e32 v48, 1.0, v48
	v_add_f32_e32 v49, 1.0, v49
	v_add_f32_e32 v50, 1.0, v50
	v_add_f32_e32 v51, 1.0, v51
	v_add_f32_e32 v52, 1.0, v52
	v_add_f32_e32 v53, 1.0, v53
	v_add_f32_e32 v54, 1.0, v54
	v_add_f32_e32 v55, 1.0, v55
	v_add_f32_e32 v56, 1.0, v56
	v_add_f32_e32 v57, 1.0, v57
	v_add_f32_e32 v58, 1.0, v58
	v_add_f32_e32 v59, 1.0, v59
	v_add_f32_e32 v60, 1.0, v60
	v_add_f32_e32 v61, 1.0, v61
	v_add_f32_e32 v62, 1.0, v62
	v_add_f32_e32 v63, 1.0, v63
	v_rcp_f32_e32 v48, v48
	v_rcp_f32_e32 v49, v49
	v_rcp_f32_e32 v50, v50
	v_rcp_f32_e32 v51, v51
	v_rcp_f32_e32 v52, v52
	v_rcp_f32_e32 v53, v53
	v_rcp_f32_e32 v54, v54
	v_rcp_f32_e32 v55, v55
	v_rcp_f32_e32 v56, v56
	v_rcp_f32_e32 v57, v57
	v_rcp_f32_e32 v58, v58
	v_rcp_f32_e32 v59, v59
	v_rcp_f32_e32 v60, v60
	v_rcp_f32_e32 v61, v61
	v_rcp_f32_e32 v62, v62
	v_rcp_f32_e32 v63, v63
	v_mul_f32_e32 v40, v48, v24
	v_mul_f32_e32 v41, v49, v25
	v_mul_f32_e32 v42, v50, v26
	v_mul_f32_e32 v43, v51, v27
	v_fmac_f32_e32 v40, v52, v112
	v_fmac_f32_e32 v41, v53, v113
	v_fmac_f32_e32 v42, v54, v114
	v_fmac_f32_e32 v43, v55, v115
	v_fmac_f32_e32 v40, v56, v128
	v_fmac_f32_e32 v41, v57, v129
	v_fmac_f32_e32 v42, v58, v130
	v_fmac_f32_e32 v43, v59, v131
	v_fmac_f32_e32 v40, v60, v144
	v_fmac_f32_e32 v41, v61, v145
	v_fmac_f32_e32 v42, v62, v146
	v_fmac_f32_e32 v43, v63, v147
	v_lshlrev_b32_e32 v48, 16, v174
	v_and_b32_e32 v49, 0xffff0000, v174
	v_lshlrev_b32_e32 v50, 16, v175
	v_and_b32_e32 v51, 0xffff0000, v175
	v_lshlrev_b32_e32 v52, 16, v182
	v_and_b32_e32 v53, 0xffff0000, v182
	v_lshlrev_b32_e32 v54, 16, v183
	v_and_b32_e32 v55, 0xffff0000, v183
	v_lshlrev_b32_e32 v56, 16, v190
	v_and_b32_e32 v57, 0xffff0000, v190
	v_lshlrev_b32_e32 v58, 16, v191
	v_and_b32_e32 v59, 0xffff0000, v191
	v_lshlrev_b32_e32 v60, 16, v198
	v_and_b32_e32 v61, 0xffff0000, v198
	v_lshlrev_b32_e32 v62, 16, v199
	v_and_b32_e32 v63, 0xffff0000, v199
	v_add_f32_e32 v48, v48, v76
	v_add_f32_e32 v49, v49, v77
	v_add_f32_e32 v50, v50, v78
	v_add_f32_e32 v51, v51, v79
	v_add_f32_e32 v52, v52, v84
	v_add_f32_e32 v53, v53, v85
	v_add_f32_e32 v54, v54, v86
	v_add_f32_e32 v55, v55, v87
	v_add_f32_e32 v56, v56, v92
	v_add_f32_e32 v57, v57, v93
	v_add_f32_e32 v58, v58, v94
	v_add_f32_e32 v59, v59, v95
	v_add_f32_e32 v60, v60, v100
	v_add_f32_e32 v61, v61, v101
	v_add_f32_e32 v62, v62, v102
	v_add_f32_e32 v63, v63, v103
	v_mul_f32_e32 v48, 0xbfb8aa3b, v48
	v_mul_f32_e32 v49, 0xbfb8aa3b, v49
	v_mul_f32_e32 v50, 0xbfb8aa3b, v50
	v_mul_f32_e32 v51, 0xbfb8aa3b, v51
	v_mul_f32_e32 v52, 0xbfb8aa3b, v52
	v_mul_f32_e32 v53, 0xbfb8aa3b, v53
	v_mul_f32_e32 v54, 0xbfb8aa3b, v54
	v_mul_f32_e32 v55, 0xbfb8aa3b, v55
	v_mul_f32_e32 v56, 0xbfb8aa3b, v56
	v_mul_f32_e32 v57, 0xbfb8aa3b, v57
	v_mul_f32_e32 v58, 0xbfb8aa3b, v58
	v_mul_f32_e32 v59, 0xbfb8aa3b, v59
	v_mul_f32_e32 v60, 0xbfb8aa3b, v60
	v_mul_f32_e32 v61, 0xbfb8aa3b, v61
	v_mul_f32_e32 v62, 0xbfb8aa3b, v62
	v_mul_f32_e32 v63, 0xbfb8aa3b, v63
	v_exp_f32_e32 v48, v48
	v_exp_f32_e32 v49, v49
	v_exp_f32_e32 v50, v50
	v_exp_f32_e32 v51, v51
	v_exp_f32_e32 v52, v52
	v_exp_f32_e32 v53, v53
	v_exp_f32_e32 v54, v54
	v_exp_f32_e32 v55, v55
	v_exp_f32_e32 v56, v56
	v_exp_f32_e32 v57, v57
	v_exp_f32_e32 v58, v58
	v_exp_f32_e32 v59, v59
	v_exp_f32_e32 v60, v60
	v_exp_f32_e32 v61, v61
	v_exp_f32_e32 v62, v62
	v_exp_f32_e32 v63, v63
	v_min_f32_e32 v48, 0x60ad78ec, v48
	v_min_f32_e32 v49, 0x60ad78ec, v49
	v_min_f32_e32 v50, 0x60ad78ec, v50
	v_min_f32_e32 v51, 0x60ad78ec, v51
	v_min_f32_e32 v52, 0x60ad78ec, v52
	v_min_f32_e32 v53, 0x60ad78ec, v53
	v_min_f32_e32 v54, 0x60ad78ec, v54
	v_min_f32_e32 v55, 0x60ad78ec, v55
	v_min_f32_e32 v56, 0x60ad78ec, v56
	v_min_f32_e32 v57, 0x60ad78ec, v57
	v_min_f32_e32 v58, 0x60ad78ec, v58
	v_min_f32_e32 v59, 0x60ad78ec, v59
	v_min_f32_e32 v60, 0x60ad78ec, v60
	v_min_f32_e32 v61, 0x60ad78ec, v61
	v_min_f32_e32 v62, 0x60ad78ec, v62
	v_min_f32_e32 v63, 0x60ad78ec, v63
	v_add_f32_e32 v48, 1.0, v48
	v_add_f32_e32 v49, 1.0, v49
	v_add_f32_e32 v50, 1.0, v50
	v_add_f32_e32 v51, 1.0, v51
	v_add_f32_e32 v52, 1.0, v52
	v_add_f32_e32 v53, 1.0, v53
	v_add_f32_e32 v54, 1.0, v54
	v_add_f32_e32 v55, 1.0, v55
	v_add_f32_e32 v56, 1.0, v56
	v_add_f32_e32 v57, 1.0, v57
	v_add_f32_e32 v58, 1.0, v58
	v_add_f32_e32 v59, 1.0, v59
	v_add_f32_e32 v60, 1.0, v60
	v_add_f32_e32 v61, 1.0, v61
	v_add_f32_e32 v62, 1.0, v62
	v_add_f32_e32 v63, 1.0, v63
	v_rcp_f32_e32 v48, v48
	v_rcp_f32_e32 v49, v49
	v_rcp_f32_e32 v50, v50
	v_rcp_f32_e32 v51, v51
	v_rcp_f32_e32 v52, v52
	v_rcp_f32_e32 v53, v53
	v_rcp_f32_e32 v54, v54
	v_rcp_f32_e32 v55, v55
	v_rcp_f32_e32 v56, v56
	v_rcp_f32_e32 v57, v57
	v_rcp_f32_e32 v58, v58
	v_rcp_f32_e32 v59, v59
	v_rcp_f32_e32 v60, v60
	v_rcp_f32_e32 v61, v61
	v_rcp_f32_e32 v62, v62
	v_rcp_f32_e32 v63, v63
	v_mul_f32_e32 v44, v48, v28
	v_mul_f32_e32 v45, v49, v29
	v_mul_f32_e32 v46, v50, v30
	v_mul_f32_e32 v47, v51, v31
	v_fmac_f32_e32 v44, v52, v116
	v_fmac_f32_e32 v45, v53, v117
	v_fmac_f32_e32 v46, v54, v118
	v_fmac_f32_e32 v47, v55, v119
	v_fmac_f32_e32 v44, v56, v132
	v_fmac_f32_e32 v45, v57, v133
	v_fmac_f32_e32 v46, v58, v134
	v_fmac_f32_e32 v47, v59, v135
	v_fmac_f32_e32 v44, v60, v148
	v_fmac_f32_e32 v45, v61, v149
	v_fmac_f32_e32 v46, v62, v150
	v_fmac_f32_e32 v47, v63, v151
	v_cvt_pk_bf16_f32 v48, v32, v33
	v_cvt_pk_bf16_f32 v49, v34, v35
	v_cvt_pk_bf16_f32 v50, v36, v37
	v_cvt_pk_bf16_f32 v51, v38, v39
	v_cvt_pk_bf16_f32 v52, v40, v41
	v_cvt_pk_bf16_f32 v53, v42, v43
	v_cvt_pk_bf16_f32 v54, v44, v45
	v_cvt_pk_bf16_f32 v55, v46, v47
	global_store_dwordx2 v203, v[48:49], s[58:59]
	global_store_dwordx2 v203, v[50:51], s[58:59] offset:32
	global_store_dwordx2 v204, v[52:53], s[58:59]
	global_store_dwordx2 v204, v[54:55], s[58:59] offset:32
	s_barrier
	s_branch .LBB0_1139
